# sparse attention tile loop: counted vmcnt waits (step-top waits cover only the mask word; K/V tile loads are waited right before their LDS store, two steps after issue)
# baseline (speedup 1.0000x reference)
.LBB0_63:
	s_add_i32 s0, s44, -3
	s_cmp_lt_u32 s0, s43
	s_cselect_b64 s[8:9], -1, 0
	s_cbranch_scc1 .Lvw_a4
	s_waitcnt vmcnt(0)
	s_branch .Lvw_a
.Lvw_a4:
	s_waitcnt vmcnt(4)
.Lvw_a:
	s_cmp_ge_u32 s0, s43
	v_mov_b64_e32 v[204:205], v[202:203]
	s_cbranch_scc1 .LBB0_65
	global_load_dwordx2 v[204:205], v[196:197], off

.LBB0_78:
	s_or_b64 exec, exec, s[0:1]
	v_cndmask_b32_e64 v174, 0, 1, s[8:9]
	v_cmp_ne_u32_e64 s[0:1], 1, v174
	s_andn2_b64 vcc, exec, s[8:9]
	s_mul_i32 s48, s45, 0x8c00
	s_cbranch_vccnz .LBB0_80
	s_and_b64 vcc, exec, s[30:31]
	s_cbranch_vccz .Lvw_a21
	s_waitcnt vmcnt(5)
	s_branch .Lvw_a2e
.Lvw_a21:
	s_waitcnt vmcnt(1)
.Lvw_a2e:
	s_add_i32 s8, s48, 0
	v_add3_u32 v174, s8, v179, v181
	ds_write_b128 v174, v[130:133]
	v_add3_u32 v174, s8, v206, v181
	ds_write_b128 v174, v[134:137]
	v_add3_u32 v174, s8, v207, v163
	v_add_u32_e32 v174, 0x4000, v174
	ds_write2_b64 v174, v[138:139], v[140:141] offset0:128 offset1:130
	v_add3_u32 v174, s8, v208, v163
	v_add_u32_e32 v174, 0x4000, v174
	ds_write2_b64 v174, v[142:143], v[144:145] offset0:128 offset1:130
.LBB0_80:
	s_add_i32 s8, s45, 1
	s_cmp_lg_u32 s45, 2
	s_cselect_b32 s50, s8, 0
	s_and_b64 vcc, exec, s[0:1]
	s_waitcnt lgkmcnt(0)
	s_barrier
	s_cbranch_vccnz .LBB0_61
	v_cndmask_b32_e64 v174, 0, 1, s[30:31]
	v_cmp_ne_u32_e64 s[8:9], 1, v174
	s_andn2_b64 vcc, exec, s[30:31]
	s_cbranch_vccnz .Lvw_b0
	s_waitcnt vmcnt(4)
	s_branch .Lvw_be

.Lvw_be:
	v_mov_b64_e32 v[202:203], v[204:205]
	s_cbranch_vccnz .LBB0_83
	global_load_dwordx2 v[202:203], v[196:197], off offset:8

.LBB0_88:
	s_cmp_gt_u32 s44, s43
	s_cbranch_scc1 .Lvw_b21
	s_waitcnt vmcnt(5)
	s_branch .Lvw_b2e
